# GEMM steps: one static s_setprio 1 for waves 0-3 (the leading half) at step entry, reset at step end; no per-phase flips
# speedup vs baseline: 1.0087x; 1.0087x over previous
.LBB0_54:
	s_add_i32 m0, s28, 0x18000
	v_lshl_add_u64 v[0:1], v[0:1], 0, s[70:71]
	s_waitcnt vmcnt(2)
	s_barrier
	global_load_lds_dwordx4 v[0:1], off
	v_lshl_add_u64 v[0:1], v[2:3], 0, s[70:71]
	s_add_i32 m0, s28, 0x1a000
	s_add_i32 s81, s28, 0x8000
	global_load_lds_dwordx4 v[0:1], off
	v_lshl_add_u64 v[0:1], v[8:9], 0, s[70:71]
	s_mov_b32 m0, s81
	s_add_i32 s82, s28, 0xa000
	global_load_lds_dwordx4 v[0:1], off
	v_lshl_add_u64 v[0:1], v[10:11], 0, s[70:71]
	s_mov_b32 m0, s82
	v_bfe_u32 v20, v13, 4, 2
	global_load_lds_dwordx4 v[0:1], off
	s_add_i32 m0, s28, 0x1c000
	v_lshl_add_u64 v[0:1], v[4:5], 0, s[70:71]
	global_load_lds_dwordx4 v[0:1], off
	v_lshl_add_u64 v[0:1], v[6:7], 0, s[70:71]
	s_add_i32 m0, s28, 0x1e000
	v_and_b32_e32 v184, 15, v13
	global_load_lds_dwordx4 v[0:1], off
	v_rcp_iflag_f32_e32 v0, v12
	v_lshlrev_b32_e32 v22, 4, v20
	v_lshlrev_b32_e32 v23, 2, v13
	s_xor_b64 s[64:65], s[0:1], -1
	v_mul_f32_e32 v0, 0x4f7ffffe, v0
	v_cvt_u32_f32_e32 v0, v0
	s_and_b32 s77, s5, 3
	s_lshr_b32 s78, s3, 6
	v_lshl_or_b32 v22, v184, 6, v22
	s_lshl_b32 s0, s19, 13
	v_and_b32_e32 v23, 32, v23
	s_lshl_b32 s79, s19, 6
	v_bitop3_b32 v24, v22, s0, v23 bitop3:0xde
	s_lshl_b32 s0, s77, 12
	s_add_i32 s84, s78, -2
	s_cmpk_lt_u32 s2, 0x100
	v_bitop3_b32 v185, v22, s0, v23 bitop3:0xde
	s_cselect_b64 s[66:67], -1, 0
	s_lshr_b32 s0, s24, 4
	v_readfirstlane_b32 s1, v0
	v_add_u32_e32 v0, v16, v14
	v_writelane_b32 v245, s0, 36
	s_sub_i32 s0, 0, s25
	v_add_lshl_u32 v0, v0, v15, 1
	v_mov_b32_e32 v1, v193
	s_waitcnt vmcnt(6)
	s_mul_i32 s0, s0, s1
	v_lshl_add_u64 v[162:163], s[30:31], 0, v[0:1]
	v_add_u32_e32 v0, v19, v17
	v_lshlrev_b32_e32 v21, 3, v20
	s_mul_hi_u32 s0, s1, s0
	v_add_lshl_u32 v0, v0, v18, 1
	v_lshl_or_b32 v186, s77, 5, v21
	v_and_b32_e32 v187, 63, v13
	s_mov_b32 s85, 0
	v_cmp_eq_u32_e64 s[36:37], 0, v20
	s_mov_b32 s19, s4
	s_add_i32 s2, s1, s0
	v_lshl_add_u64 v[164:165], s[30:31], 0, v[0:1]
	v_add_u32_e32 v188, 0, v24
	v_readfirstlane_b32 s33, v195
	s_nop 3
	s_lshr_b32 s33, s33, 6
	s_cmp_ge_u32 s33, 4
	s_cbranch_scc1 .Lmy_prio_done
	s_setprio 1
